# attention: K-fragment LDS addresses computed once per tile (6 v_add) with immediate kb offsets instead of 24 v_add per tile
# speedup vs baseline: 1.0160x; 1.0160x over previous
.LBB0_999:
	s_add_i32 s28, s29, 1
	s_cmp_lt_u32 s29, 3
	s_cselect_b32 s8, s27, s13
	s_ashr_i32 s9, s8, 31
	s_mul_i32 s10, s8, 0xc00
	s_mul_hi_i32 s11, s8, 0xc00
	s_add_u32 s10, s16, s10
	s_addc_u32 s11, s17, s11
	s_lshl_b64 s[8:9], s[8:9], 1
	s_add_u32 vcc_lo, s18, s8
	s_addc_u32 vcc_hi, s19, s9
	s_bitcmp1_b32 s28, 0
	s_cselect_b32 s12, 0xa800, 0
	v_readfirstlane_b32 s30, v181
	s_add_i32 s30, s30, s12
	s_bitcmp1_b32 s29, 0
	s_cselect_b32 s8, 0xa800, 0
	v_add_u32_e32 v159, s8, v198
	v_add_u32_e32 v173, s8, v199
	v_add_u32_e32 v175, s8, v200
	v_add_u32_e32 v177, s8, v201
	v_add_u32_e32 v179, s8, v225
	v_add_u32_e32 v195, s8, v226
	ds_read_b128 v[116:119], v159
	ds_read_b128 v[124:127], v173
	ds_read_b128 v[128:131], v175
	ds_read_b128 v[136:139], v177
	ds_read_b128 v[132:135], v179
	ds_read_b128 v[140:143], v195
	s_waitcnt lgkmcnt(5)
	v_mfma_f32_16x16x32_bf16 v[112:115], v[116:119], v[104:107], 0
	v_mfma_f32_16x16x32_bf16 v[120:123], v[116:119], v[108:111], 0
	ds_read_b128 v[204:207], v159 offset:6144
	s_waitcnt lgkmcnt(5)
	v_mfma_f32_16x16x32_bf16 v[112:115], v[124:127], v[96:99], v[112:115]
	v_mfma_f32_16x16x32_bf16 v[120:123], v[124:127], v[100:103], v[120:123]
	ds_read_b128 v[208:211], v173 offset:6144
	s_add_i32 m0, s30, 0x0
	s_waitcnt lgkmcnt(5)
	v_mfma_f32_16x16x32_bf16 v[112:115], v[128:131], v[88:91], v[112:115]
	v_mfma_f32_16x16x32_bf16 v[120:123], v[128:131], v[92:95], v[120:123]
	global_load_lds_dwordx4 v158, s[10:11]
	ds_read_b128 v[128:131], v175 offset:6144
	s_waitcnt lgkmcnt(5)
	v_mfma_f32_16x16x32_bf16 v[112:115], v[136:139], v[80:83], v[112:115]
	v_mfma_f32_16x16x32_bf16 v[120:123], v[136:139], v[84:87], v[120:123]
	ds_read_b128 v[136:139], v177 offset:6144
	s_waitcnt lgkmcnt(5)
	v_mfma_f32_16x16x32_bf16 v[112:115], v[132:135], v[72:75], v[112:115]
	v_mfma_f32_16x16x32_bf16 v[120:123], v[132:135], v[76:79], v[120:123]
	ds_read_b128 v[132:135], v179 offset:6144
	s_add_i32 m0, s30, 0x2000
	s_waitcnt lgkmcnt(5)
	v_mfma_f32_16x16x32_bf16 v[112:115], v[140:143], v[64:67], v[112:115]
	v_mfma_f32_16x16x32_bf16 v[120:123], v[140:143], v[68:71], v[120:123]
	global_load_lds_dwordx4 v172, s[10:11]
	ds_read_b128 v[140:143], v195 offset:6144
	s_waitcnt lgkmcnt(5)
	v_mfma_f32_16x16x32_bf16 v[116:119], v[204:207], v[104:107], 0
	v_mfma_f32_16x16x32_bf16 v[124:127], v[204:207], v[108:111], 0
	ds_read_b128 v[204:207], v159 offset:12288
	s_waitcnt lgkmcnt(5)
	v_mfma_f32_16x16x32_bf16 v[116:119], v[208:211], v[96:99], v[116:119]
	v_mfma_f32_16x16x32_bf16 v[124:127], v[208:211], v[100:103], v[124:127]
	ds_read_b128 v[208:211], v173 offset:12288
	s_add_i32 m0, s30, 0x4000
	s_waitcnt lgkmcnt(5)
	v_mfma_f32_16x16x32_bf16 v[116:119], v[128:131], v[88:91], v[116:119]
	v_mfma_f32_16x16x32_bf16 v[124:127], v[128:131], v[92:95], v[124:127]
	global_load_lds_dwordx4 v174, s[10:11]
	s_waitcnt lgkmcnt(4)
	v_mfma_f32_16x16x32_bf16 v[116:119], v[136:139], v[80:83], v[116:119]
	v_mfma_f32_16x16x32_bf16 v[124:127], v[136:139], v[84:87], v[124:127]
	s_waitcnt lgkmcnt(3)
	v_mfma_f32_16x16x32_bf16 v[116:119], v[132:135], v[72:75], v[116:119]
	v_mfma_f32_16x16x32_bf16 v[124:127], v[132:135], v[76:79], v[124:127]
	ds_read_b128 v[132:135], v175 offset:12288
	s_add_i32 m0, s30, 0x6000
	s_waitcnt lgkmcnt(3)
	v_mfma_f32_16x16x32_bf16 v[116:119], v[140:143], v[64:67], v[116:119]
	v_mfma_f32_16x16x32_bf16 v[124:127], v[140:143], v[68:71], v[124:127]
	global_load_lds_dwordx4 v176, vcc
	ds_read_b128 v[140:143], v177 offset:12288
	s_waitcnt lgkmcnt(3)
	v_mfma_f32_16x16x32_bf16 v[136:139], v[204:207], v[104:107], 0
	v_mfma_f32_16x16x32_bf16 v[128:131], v[204:207], v[108:111], 0
	ds_read_b128 v[204:207], v179 offset:12288
	s_waitcnt lgkmcnt(3)
	v_mfma_f32_16x16x32_bf16 v[136:139], v[208:211], v[96:99], v[136:139]
	v_mfma_f32_16x16x32_bf16 v[128:131], v[208:211], v[100:103], v[128:131]
	ds_read_b128 v[208:211], v195 offset:12288
	s_add_i32 m0, s30, 0x8000
	s_waitcnt lgkmcnt(3)
	v_mfma_f32_16x16x32_bf16 v[136:139], v[132:135], v[88:91], v[136:139]
	v_mfma_f32_16x16x32_bf16 v[128:131], v[132:135], v[92:95], v[128:131]
	global_load_lds_dwordx4 v178, vcc
	s_waitcnt lgkmcnt(2)
	v_mfma_f32_16x16x32_bf16 v[136:139], v[140:143], v[80:83], v[136:139]
	v_mfma_f32_16x16x32_bf16 v[128:131], v[140:143], v[84:87], v[128:131]
	s_waitcnt lgkmcnt(1)
	v_mfma_f32_16x16x32_bf16 v[136:139], v[204:207], v[72:75], v[136:139]
	v_mfma_f32_16x16x32_bf16 v[128:131], v[204:207], v[76:79], v[128:131]
	ds_read_b128 v[204:207], v159 offset:18432
	s_waitcnt lgkmcnt(1)
	v_mfma_f32_16x16x32_bf16 v[136:139], v[208:211], v[64:67], v[136:139]
	v_mfma_f32_16x16x32_bf16 v[128:131], v[208:211], v[68:71], v[128:131]
	s_cmp_lg_u64 s[6:7], 0
	s_cbranch_scc0 .Lat_v2skip
	s_add_i32 m0, s30, 0xa000
	s_nop 0
	global_load_lds_dwordx4 v160, vcc
.Lat_v2skip:
	ds_read_b128 v[208:211], v173 offset:18432
	s_waitcnt lgkmcnt(1)
	v_mfma_f32_16x16x32_bf16 v[140:143], v[204:207], v[104:107], 0
	v_mfma_f32_16x16x32_bf16 v[132:135], v[204:207], v[108:111], 0
	ds_read_b128 v[204:207], v175 offset:18432
	s_waitcnt lgkmcnt(1)
	v_mfma_f32_16x16x32_bf16 v[140:143], v[208:211], v[96:99], v[140:143]
	v_mfma_f32_16x16x32_bf16 v[132:135], v[208:211], v[100:103], v[132:135]
	ds_read_b128 v[208:211], v177 offset:18432
	s_waitcnt lgkmcnt(1)
	v_mfma_f32_16x16x32_bf16 v[140:143], v[204:207], v[88:91], v[140:143]
	v_mfma_f32_16x16x32_bf16 v[132:135], v[204:207], v[92:95], v[132:135]
	ds_read_b128 v[204:207], v179 offset:18432
	s_waitcnt lgkmcnt(1)
	v_mfma_f32_16x16x32_bf16 v[140:143], v[208:211], v[80:83], v[140:143]
	v_mfma_f32_16x16x32_bf16 v[132:135], v[208:211], v[84:87], v[132:135]
	ds_read_b128 v[208:211], v195 offset:18432
	s_waitcnt lgkmcnt(1)
	v_mfma_f32_16x16x32_bf16 v[140:143], v[204:207], v[72:75], v[140:143]
	v_mfma_f32_16x16x32_bf16 v[132:135], v[204:207], v[76:79], v[132:135]
	s_waitcnt lgkmcnt(0)
	v_mfma_f32_16x16x32_bf16 v[140:143], v[208:211], v[64:67], v[140:143]
	v_mfma_f32_16x16x32_bf16 v[132:135], v[208:211], v[68:71], v[132:135]
	s_nop 7
	v_fmamk_f32 v112, v112, 0x3dd53b94, v157
	v_fmamk_f32 v113, v113, 0x3dd53b94, v157
	v_fmamk_f32 v114, v114, 0x3dd53b94, v157
	v_exp_f32_e32 v112, v112
	v_fmamk_f32 v115, v115, 0x3dd53b94, v157
	v_exp_f32_e32 v113, v113
	v_fmamk_f32 v116, v116, 0x3dd53b94, v157
	v_exp_f32_e32 v114, v114
	v_fmamk_f32 v117, v117, 0x3dd53b94, v157
	v_exp_f32_e32 v115, v115
	v_fmamk_f32 v118, v118, 0x3dd53b94, v157
	v_exp_f32_e32 v116, v116
	v_fmamk_f32 v119, v119, 0x3dd53b94, v157
	v_exp_f32_e32 v117, v117
	v_fmamk_f32 v136, v136, 0x3dd53b94, v157
	v_exp_f32_e32 v118, v118
	v_fmamk_f32 v137, v137, 0x3dd53b94, v157
	v_exp_f32_e32 v119, v119
	v_fmamk_f32 v138, v138, 0x3dd53b94, v157
	v_exp_f32_e32 v136, v136
	v_fmamk_f32 v139, v139, 0x3dd53b94, v157
	v_exp_f32_e32 v137, v137
	v_fmamk_f32 v140, v140, 0x3dd53b94, v157
	v_exp_f32_e32 v138, v138
	v_fmamk_f32 v141, v141, 0x3dd53b94, v157
	v_exp_f32_e32 v139, v139
	v_fmamk_f32 v142, v142, 0x3dd53b94, v157
	v_exp_f32_e32 v140, v140
	v_fmamk_f32 v143, v143, 0x3dd53b94, v157
	v_exp_f32_e32 v141, v141
	v_exp_f32_e32 v142, v142
	v_exp_f32_e32 v143, v143
	s_nop 0
	v_add_f32_e32 v204, v112, v113
	v_add_f32_e32 v205, v114, v115
	v_add_f32_e32 v206, v116, v117
	v_add_f32_e32 v207, v118, v119
	v_add_f32_e32 v208, v136, v137
	v_add_f32_e32 v209, v138, v139
	v_add_f32_e32 v210, v140, v141
	v_add_f32_e32 v211, v142, v143
	v_add_f32_e32 v204, v204, v205
	v_add_f32_e32 v206, v206, v207
	v_add_f32_e32 v208, v208, v209
	v_add_f32_e32 v210, v210, v211
	v_add_f32_e32 v204, v204, v206
	v_add_f32_e32 v208, v208, v210
	v_add_f32_e32 v195, v204, v208
	v_fmamk_f32 v120, v120, 0x3dd53b94, v155
	v_fmamk_f32 v121, v121, 0x3dd53b94, v155
	v_fmamk_f32 v122, v122, 0x3dd53b94, v155
	v_exp_f32_e32 v120, v120
	v_fmamk_f32 v123, v123, 0x3dd53b94, v155
	v_exp_f32_e32 v121, v121
	v_fmamk_f32 v124, v124, 0x3dd53b94, v155
	v_exp_f32_e32 v122, v122
	v_fmamk_f32 v125, v125, 0x3dd53b94, v155
	v_exp_f32_e32 v123, v123
	v_fmamk_f32 v126, v126, 0x3dd53b94, v155
	v_exp_f32_e32 v124, v124
	v_fmamk_f32 v127, v127, 0x3dd53b94, v155
	v_exp_f32_e32 v125, v125
	v_fmamk_f32 v128, v128, 0x3dd53b94, v155
	v_exp_f32_e32 v126, v126
	v_fmamk_f32 v129, v129, 0x3dd53b94, v155
	v_exp_f32_e32 v127, v127
	v_fmamk_f32 v130, v130, 0x3dd53b94, v155
	v_exp_f32_e32 v128, v128
	v_fmamk_f32 v131, v131, 0x3dd53b94, v155
	v_exp_f32_e32 v129, v129
	v_fmamk_f32 v132, v132, 0x3dd53b94, v155
	v_exp_f32_e32 v130, v130
	v_fmamk_f32 v133, v133, 0x3dd53b94, v155
	v_exp_f32_e32 v131, v131
	v_fmamk_f32 v134, v134, 0x3dd53b94, v155
	v_exp_f32_e32 v132, v132
	v_fmamk_f32 v135, v135, 0x3dd53b94, v155
	v_exp_f32_e32 v133, v133
	v_exp_f32_e32 v134, v134
	v_exp_f32_e32 v135, v135
	s_nop 0
	v_add_f32_e32 v204, v120, v121
	v_add_f32_e32 v205, v122, v123
	v_add_f32_e32 v206, v124, v125
	v_add_f32_e32 v207, v126, v127
	v_add_f32_e32 v208, v128, v129
	v_add_f32_e32 v209, v130, v131
	v_add_f32_e32 v210, v132, v133
	v_add_f32_e32 v211, v134, v135
	v_add_f32_e32 v204, v204, v205
	v_add_f32_e32 v206, v206, v207
	v_add_f32_e32 v208, v208, v209
	v_add_f32_e32 v210, v210, v211
	v_add_f32_e32 v204, v204, v206
	v_add_f32_e32 v208, v208, v210
	v_add_f32_e32 v230, v204, v208
	v_add_f32_e32 v211, v195, v230
	v_cmp_ge_f32_e32 vcc, 0x47800000, v211
	s_cmp_eq_u64 vcc, exec
	s_cbranch_scc0 .Lattn_slow
	v_add_f32_e32 v156, v156, v195
	v_add_f32_e32 v154, v154, v230
	v_cvt_pk_bf16_f32 v119, v118, v119
	v_cvt_pk_bf16_f32 v118, v116, v117
	v_cvt_pk_bf16_f32 v116, v112, v113
	v_cvt_pk_bf16_f32 v117, v114, v115
	v_cvt_pk_bf16_f32 v112, v136, v137
	v_cvt_pk_bf16_f32 v113, v138, v139
	v_cvt_pk_bf16_f32 v114, v140, v141
	v_cvt_pk_bf16_f32 v115, v142, v143
	v_cvt_pk_bf16_f32 v127, v126, v127
	v_cvt_pk_bf16_f32 v126, v124, v125
	v_cvt_pk_bf16_f32 v124, v120, v121
	v_cvt_pk_bf16_f32 v125, v122, v123
	v_cvt_pk_bf16_f32 v120, v128, v129
	v_cvt_pk_bf16_f32 v121, v130, v131
	v_cvt_pk_bf16_f32 v122, v132, v133
	v_cvt_pk_bf16_f32 v123, v134, v135

.Lattn_slow:
	v_add_u32_e32 v159, s8, v198
	v_add_u32_e32 v173, s8, v199
	v_add_u32_e32 v175, s8, v200
	v_add_u32_e32 v177, s8, v201
	v_add_u32_e32 v179, s8, v225
	v_add_u32_e32 v195, s8, v226
	ds_read_b128 v[116:119], v159
	ds_read_b128 v[124:127], v173
	ds_read_b128 v[128:131], v175
	ds_read_b128 v[136:139], v177
	ds_read_b128 v[132:135], v179
	ds_read_b128 v[140:143], v195
	s_waitcnt lgkmcnt(5)
	v_mfma_f32_16x16x32_bf16 v[112:115], v[116:119], v[104:107], 0
	v_mfma_f32_16x16x32_bf16 v[120:123], v[116:119], v[108:111], 0
	ds_read_b128 v[204:207], v159 offset:6144
	s_waitcnt lgkmcnt(5)
	v_mfma_f32_16x16x32_bf16 v[112:115], v[124:127], v[96:99], v[112:115]
	v_mfma_f32_16x16x32_bf16 v[120:123], v[124:127], v[100:103], v[120:123]
	ds_read_b128 v[208:211], v173 offset:6144
	s_waitcnt lgkmcnt(5)
	v_mfma_f32_16x16x32_bf16 v[112:115], v[128:131], v[88:91], v[112:115]
	v_mfma_f32_16x16x32_bf16 v[120:123], v[128:131], v[92:95], v[120:123]
	ds_read_b128 v[128:131], v175 offset:6144
	s_waitcnt lgkmcnt(5)
	v_mfma_f32_16x16x32_bf16 v[112:115], v[136:139], v[80:83], v[112:115]
	v_mfma_f32_16x16x32_bf16 v[120:123], v[136:139], v[84:87], v[120:123]
	ds_read_b128 v[136:139], v177 offset:6144
	s_waitcnt lgkmcnt(5)
	v_mfma_f32_16x16x32_bf16 v[112:115], v[132:135], v[72:75], v[112:115]
	v_mfma_f32_16x16x32_bf16 v[120:123], v[132:135], v[76:79], v[120:123]
	ds_read_b128 v[132:135], v179 offset:6144
	s_waitcnt lgkmcnt(5)
	v_mfma_f32_16x16x32_bf16 v[112:115], v[140:143], v[64:67], v[112:115]
	v_mfma_f32_16x16x32_bf16 v[120:123], v[140:143], v[68:71], v[120:123]
	ds_read_b128 v[140:143], v195 offset:6144
	s_waitcnt lgkmcnt(5)
	v_mfma_f32_16x16x32_bf16 v[116:119], v[204:207], v[104:107], 0
	v_mfma_f32_16x16x32_bf16 v[124:127], v[204:207], v[108:111], 0
	ds_read_b128 v[204:207], v159 offset:12288
	s_waitcnt lgkmcnt(5)
	v_mfma_f32_16x16x32_bf16 v[116:119], v[208:211], v[96:99], v[116:119]
	v_mfma_f32_16x16x32_bf16 v[124:127], v[208:211], v[100:103], v[124:127]
	ds_read_b128 v[208:211], v173 offset:12288
	s_waitcnt lgkmcnt(5)
	v_mfma_f32_16x16x32_bf16 v[116:119], v[128:131], v[88:91], v[116:119]
	v_mfma_f32_16x16x32_bf16 v[124:127], v[128:131], v[92:95], v[124:127]
	s_waitcnt lgkmcnt(4)
	v_mfma_f32_16x16x32_bf16 v[116:119], v[136:139], v[80:83], v[116:119]
	v_mfma_f32_16x16x32_bf16 v[124:127], v[136:139], v[84:87], v[124:127]
	s_waitcnt lgkmcnt(3)
	v_mfma_f32_16x16x32_bf16 v[116:119], v[132:135], v[72:75], v[116:119]
	v_mfma_f32_16x16x32_bf16 v[124:127], v[132:135], v[76:79], v[124:127]
	ds_read_b128 v[132:135], v175 offset:12288
	s_waitcnt lgkmcnt(3)
	v_mfma_f32_16x16x32_bf16 v[116:119], v[140:143], v[64:67], v[116:119]
	v_mfma_f32_16x16x32_bf16 v[124:127], v[140:143], v[68:71], v[124:127]
	ds_read_b128 v[140:143], v177 offset:12288
	s_waitcnt lgkmcnt(3)
	v_mfma_f32_16x16x32_bf16 v[136:139], v[204:207], v[104:107], 0
	v_mfma_f32_16x16x32_bf16 v[128:131], v[204:207], v[108:111], 0
	ds_read_b128 v[204:207], v179 offset:12288
	s_waitcnt lgkmcnt(3)
	v_mfma_f32_16x16x32_bf16 v[136:139], v[208:211], v[96:99], v[136:139]
	v_mfma_f32_16x16x32_bf16 v[128:131], v[208:211], v[100:103], v[128:131]
	ds_read_b128 v[208:211], v195 offset:12288
	s_waitcnt lgkmcnt(3)
	v_mfma_f32_16x16x32_bf16 v[136:139], v[132:135], v[88:91], v[136:139]
	v_mfma_f32_16x16x32_bf16 v[128:131], v[132:135], v[92:95], v[128:131]
	s_waitcnt lgkmcnt(2)
	v_mfma_f32_16x16x32_bf16 v[136:139], v[140:143], v[80:83], v[136:139]
	v_mfma_f32_16x16x32_bf16 v[128:131], v[140:143], v[84:87], v[128:131]
	s_waitcnt lgkmcnt(1)
	v_mfma_f32_16x16x32_bf16 v[136:139], v[204:207], v[72:75], v[136:139]
	v_mfma_f32_16x16x32_bf16 v[128:131], v[204:207], v[76:79], v[128:131]
	ds_read_b128 v[204:207], v159 offset:18432
	s_waitcnt lgkmcnt(1)
	v_mfma_f32_16x16x32_bf16 v[136:139], v[208:211], v[64:67], v[136:139]
	v_mfma_f32_16x16x32_bf16 v[128:131], v[208:211], v[68:71], v[128:131]
	ds_read_b128 v[208:211], v173 offset:18432
	s_waitcnt lgkmcnt(1)
	v_mfma_f32_16x16x32_bf16 v[140:143], v[204:207], v[104:107], 0
	v_mfma_f32_16x16x32_bf16 v[132:135], v[204:207], v[108:111], 0
	ds_read_b128 v[204:207], v175 offset:18432
	s_waitcnt lgkmcnt(1)
	v_mfma_f32_16x16x32_bf16 v[140:143], v[208:211], v[96:99], v[140:143]
	v_mfma_f32_16x16x32_bf16 v[132:135], v[208:211], v[100:103], v[132:135]
	ds_read_b128 v[208:211], v177 offset:18432
	s_waitcnt lgkmcnt(1)
	v_mfma_f32_16x16x32_bf16 v[140:143], v[204:207], v[88:91], v[140:143]
	v_mfma_f32_16x16x32_bf16 v[132:135], v[204:207], v[92:95], v[132:135]
	ds_read_b128 v[204:207], v179 offset:18432
	s_waitcnt lgkmcnt(1)
	v_mfma_f32_16x16x32_bf16 v[140:143], v[208:211], v[80:83], v[140:143]
	v_mfma_f32_16x16x32_bf16 v[132:135], v[208:211], v[84:87], v[132:135]
	ds_read_b128 v[208:211], v195 offset:18432
	s_waitcnt lgkmcnt(1)
	v_mfma_f32_16x16x32_bf16 v[140:143], v[204:207], v[72:75], v[140:143]
	v_mfma_f32_16x16x32_bf16 v[132:135], v[204:207], v[76:79], v[132:135]
	s_waitcnt lgkmcnt(0)
	v_mfma_f32_16x16x32_bf16 v[140:143], v[208:211], v[64:67], v[140:143]
	v_mfma_f32_16x16x32_bf16 v[132:135], v[208:211], v[68:71], v[132:135]
	s_nop 7
	v_max_f32_e32 v157, v112, v112
	v_max_f32_e32 v195, v114, v114
	v_max_f32_e32 v155, v113, v113
	v_max_f32_e32 v155, v157, v155
	v_max_f32_e32 v157, v115, v115
	v_max_f32_e32 v157, v195, v157
	v_max_f32_e32 v195, v119, v119
	v_max_f32_e32 v204, v118, v118
	v_max_f32_e32 v195, v204, v195
	v_max3_f32 v195, v116, v117, v195
	v_max3_f32 v155, v155, v157, v195
	v_max_f32_e32 v157, v139, v139
	v_max_f32_e32 v195, v138, v138
	v_max_f32_e32 v157, v195, v157
	v_max_f32_e32 v195, v143, v143
	v_max_f32_e32 v204, v142, v142
	v_max_f32_e32 v195, v204, v195
	v_max3_f32 v157, v136, v137, v157
	v_max3_f32 v195, v140, v141, v195
	v_max3_f32 v155, v155, v157, v195
	v_sub_f32_e32 v157, v155, v162
	v_cmp_ge_f32_e32 vcc, s89, v157
	s_cmp_eq_u64 vcc, exec
	s_cbranch_scc1 .LBB0_1005
	v_and_b32_e32 v195, 64, v227
	v_xor_b32_e32 v157, 16, v227
	v_add_u32_e32 v195, 64, v195
	v_cmp_lt_i32_e32 vcc, v157, v195
	s_nop 1
	v_cndmask_b32_e32 v157, v227, v157, vcc
	v_lshlrev_b32_e32 v157, 2, v157
	ds_bpermute_b32 v157, v157, v155
	v_max_f32_e32 v155, v155, v155
	s_waitcnt lgkmcnt(0)
	v_max_f32_e32 v157, v157, v157
	v_max_f32_e32 v155, v155, v157
	v_xor_b32_e32 v157, 32, v227
	v_cmp_lt_i32_e32 vcc, v157, v195
	s_nop 1
	v_cndmask_b32_e32 v157, v227, v157, vcc
	v_lshlrev_b32_e32 v157, 2, v157
	ds_bpermute_b32 v157, v157, v155
	s_waitcnt lgkmcnt(0)
	v_max3_f32 v155, v162, v155, v157
	v_sub_f32_e32 v157, v162, v155
	v_mul_f32_e32 v157, 0x3dd53b94, v157
	v_exp_f32_e32 v162, v157
	s_nop 0
	v_mul_f32_e32 v156, v156, v162
	v_pk_mul_f32 v[62:63], v[62:63], v[162:163] op_sel_hi:[1,0]
	v_pk_mul_f32 v[60:61], v[60:61], v[162:163] op_sel_hi:[1,0]
	v_pk_mul_f32 v[54:55], v[54:55], v[162:163] op_sel_hi:[1,0]
	v_pk_mul_f32 v[52:53], v[52:53], v[162:163] op_sel_hi:[1,0]
	v_pk_mul_f32 v[46:47], v[46:47], v[162:163] op_sel_hi:[1,0]
	v_pk_mul_f32 v[44:45], v[44:45], v[162:163] op_sel_hi:[1,0]
	v_pk_mul_f32 v[38:39], v[38:39], v[162:163] op_sel_hi:[1,0]
	v_pk_mul_f32 v[36:37], v[36:37], v[162:163] op_sel_hi:[1,0]
	v_pk_mul_f32 v[26:27], v[26:27], v[162:163] op_sel_hi:[1,0]
	v_pk_mul_f32 v[24:25], v[24:25], v[162:163] op_sel_hi:[1,0]
	v_pk_mul_f32 v[18:19], v[18:19], v[162:163] op_sel_hi:[1,0]
	v_pk_mul_f32 v[16:17], v[16:17], v[162:163] op_sel_hi:[1,0]
	v_pk_mul_f32 v[10:11], v[10:11], v[162:163] op_sel_hi:[1,0]
	v_pk_mul_f32 v[8:9], v[8:9], v[162:163] op_sel_hi:[1,0]
	v_pk_mul_f32 v[2:3], v[2:3], v[162:163] op_sel_hi:[1,0]
	v_pk_mul_f32 v[0:1], v[0:1], v[162:163] op_sel_hi:[1,0]
	v_mov_b32_e32 v162, v155
